# in-projection GEMM epilogue (prompt instance): bf16 column groups paired with v_permlane16_swap, 16 B stores, added to the ff1 epilogue widening
# speedup vs baseline: 1.0270x; 1.0038x over previous
; DI unsigned cvtpk(float lo, float hi) { f32x2_t v = {lo, hi}; bf16x2_t b = __builtin_convertvector(v, bf16x2_t); return __builtin_bit_cast(unsigned, b); }
;     DI void operator()(const f32x4 (&acc)[2][2][4][2], const Unit& u, int wr, int wc, int fr, int fq) const {
;     ...
;                 for (int m = 0; m < 4; ++m) { const size_t rr = (size_t)(row0 + ai * HALF + m * 16); bf16_t* rp = (u.pn < 16 ? P + rr * PP + u.pn * BM : Z + rr * 1024 + (u.pn - 16) * BM) + colt;
; #pragma unroll
;                     for (int bj = 0; bj < 2; ++bj)
; #pragma unroll
;                         for (int n = 0; n < 2; ++n) { const f32x4 v = acc[ai][bj][m][n]; u32x2 w; w.x = cvtpk(v[0], v[1]); w.y = cvtpk(v[2], v[3]); *(u32x2*)(rp + bj * HALF + n * 16) = w; } }
.LBB0_230:
	v_and_b32_e32 v132, 4, v134
	v_mul_u32_u24_e32 v132, 6, v132
	v_lshl_add_u32 v132, v134, 1, v132
	v_lshl_add_u64 v[154:155], v[154:155], 0, v[132:133]
	v_cvt_pk_bf16_f32 v123, v122, v123
	v_cvt_pk_bf16_f32 v122, v120, v121
	v_cvt_pk_bf16_f32 v120, v124, v125
	v_cvt_pk_bf16_f32 v121, v126, v127
	v_cvt_pk_bf16_f32 v115, v114, v115
	v_cvt_pk_bf16_f32 v114, v112, v113
	v_cvt_pk_bf16_f32 v112, v116, v117
	v_cvt_pk_bf16_f32 v113, v118, v119
	s_nop 1
	v_permlane16_swap_b32_e32 v120, v122
	v_permlane16_swap_b32_e32 v121, v123
	v_permlane16_swap_b32_e32 v112, v114
	v_permlane16_swap_b32_e32 v113, v115
	global_store_dwordx4 v[154:155], v[120:123], off
	global_store_dwordx4 v[154:155], v[112:115], off offset:256
	s_nop 1
	v_cndmask_b32_e64 v112, 0, 1, s[38:39]
	v_ashrrev_i32_e32 v153, 31, v152
	v_cmp_ne_u32_e64 s[4:5], 1, v112
	s_andn2_b64 vcc, exec, s[38:39]
	s_mov_b64 s[38:39], -1
	s_cbranch_vccnz .LBB0_232
	v_lshlrev_b64 v[112:113], 11, v[152:153]
	v_lshl_add_u64 v[112:113], s[10:11], 0, v[112:113]
	s_mov_b32 s27, s81
	v_lshl_add_u64 v[112:113], s[26:27], 1, v[112:113]
	v_lshl_add_u64 v[112:113], v[112:113], 0, s[16:17]
	s_mov_b64 s[38:39], 0

; DI unsigned cvtpk(float lo, float hi) { f32x2_t v = {lo, hi}; bf16x2_t b = __builtin_convertvector(v, bf16x2_t); return __builtin_bit_cast(unsigned, b); }
;     DI void operator()(const f32x4 (&acc)[2][2][4][2], const Unit& u, int wr, int wc, int fr, int fq) const {
;     ...
;                 for (int m = 0; m < 4; ++m) { const size_t rr = (size_t)(row0 + ai * HALF + m * 16); bf16_t* rp = (u.pn < 16 ? P + rr * PP + u.pn * BM : Z + rr * 1024 + (u.pn - 16) * BM) + colt;
; #pragma unroll
;                     for (int bj = 0; bj < 2; ++bj)
; #pragma unroll
;                         for (int n = 0; n < 2; ++n) { const f32x4 v = acc[ai][bj][m][n]; u32x2 w; w.x = cvtpk(v[0], v[1]); w.y = cvtpk(v[2], v[3]); *(u32x2*)(rp + bj * HALF + n * 16) = w; } }
.LBB0_234:
	v_lshl_add_u64 v[112:113], v[112:113], 0, v[132:133]
	v_ashrrev_i32_e32 v151, 31, v150
	s_and_b64 vcc, exec, s[4:5]
	s_mov_b64 s[38:39], -1
	v_cvt_pk_bf16_f32 v107, v106, v107
	v_cvt_pk_bf16_f32 v106, v104, v105
	v_cvt_pk_bf16_f32 v104, v108, v109
	v_cvt_pk_bf16_f32 v105, v110, v111
	v_cvt_pk_bf16_f32 v99, v98, v99
	v_cvt_pk_bf16_f32 v98, v96, v97
	v_cvt_pk_bf16_f32 v96, v100, v101
	v_cvt_pk_bf16_f32 v97, v102, v103
	s_nop 1
	v_permlane16_swap_b32_e32 v104, v106
	v_permlane16_swap_b32_e32 v105, v107
	v_permlane16_swap_b32_e32 v96, v98
	v_permlane16_swap_b32_e32 v97, v99
	global_store_dwordx4 v[112:113], v[104:107], off
	global_store_dwordx4 v[112:113], v[96:99], off offset:256
	s_nop 1
	s_cbranch_vccnz .LBB0_236
	v_lshlrev_b64 v[96:97], 11, v[150:151]
	v_lshl_add_u64 v[96:97], s[10:11], 0, v[96:97]
	s_mov_b32 s27, s81
	v_lshl_add_u64 v[96:97], s[26:27], 1, v[96:97]
	v_lshl_add_u64 v[96:97], v[96:97], 0, s[16:17]
	s_mov_b64 s[38:39], 0

; DI unsigned cvtpk(float lo, float hi) { f32x2_t v = {lo, hi}; bf16x2_t b = __builtin_convertvector(v, bf16x2_t); return __builtin_bit_cast(unsigned, b); }
;     DI void operator()(const f32x4 (&acc)[2][2][4][2], const Unit& u, int wr, int wc, int fr, int fq) const {
;     ...
;                 for (int m = 0; m < 4; ++m) { const size_t rr = (size_t)(row0 + ai * HALF + m * 16); bf16_t* rp = (u.pn < 16 ? P + rr * PP + u.pn * BM : Z + rr * 1024 + (u.pn - 16) * BM) + colt;
; #pragma unroll
;                     for (int bj = 0; bj < 2; ++bj)
; #pragma unroll
;                         for (int n = 0; n < 2; ++n) { const f32x4 v = acc[ai][bj][m][n]; u32x2 w; w.x = cvtpk(v[0], v[1]); w.y = cvtpk(v[2], v[3]); *(u32x2*)(rp + bj * HALF + n * 16) = w; } }
.LBB0_238:
	v_lshl_add_u64 v[96:97], v[96:97], 0, v[132:133]
	v_ashrrev_i32_e32 v149, 31, v148
	s_and_b64 vcc, exec, s[4:5]
	s_mov_b64 s[38:39], -1
	v_cvt_pk_bf16_f32 v91, v90, v91
	v_cvt_pk_bf16_f32 v90, v88, v89
	v_cvt_pk_bf16_f32 v88, v92, v93
	v_cvt_pk_bf16_f32 v89, v94, v95
	v_cvt_pk_bf16_f32 v83, v82, v83
	v_cvt_pk_bf16_f32 v82, v80, v81
	v_cvt_pk_bf16_f32 v80, v84, v85
	v_cvt_pk_bf16_f32 v81, v86, v87
	s_nop 1
	v_permlane16_swap_b32_e32 v88, v90
	v_permlane16_swap_b32_e32 v89, v91
	v_permlane16_swap_b32_e32 v80, v82
	v_permlane16_swap_b32_e32 v81, v83
	global_store_dwordx4 v[96:97], v[88:91], off
	global_store_dwordx4 v[96:97], v[80:83], off offset:256
	s_nop 1
	s_cbranch_vccnz .LBB0_240
	v_lshlrev_b64 v[80:81], 11, v[148:149]
	v_lshl_add_u64 v[80:81], s[10:11], 0, v[80:81]
	s_mov_b32 s27, s81
	v_lshl_add_u64 v[80:81], s[26:27], 1, v[80:81]
	v_lshl_add_u64 v[80:81], v[80:81], 0, s[16:17]
	s_mov_b64 s[38:39], 0

; DI unsigned cvtpk(float lo, float hi) { f32x2_t v = {lo, hi}; bf16x2_t b = __builtin_convertvector(v, bf16x2_t); return __builtin_bit_cast(unsigned, b); }
;     DI void operator()(const f32x4 (&acc)[2][2][4][2], const Unit& u, int wr, int wc, int fr, int fq) const {
;     ...
;                 for (int m = 0; m < 4; ++m) { const size_t rr = (size_t)(row0 + ai * HALF + m * 16); bf16_t* rp = (u.pn < 16 ? P + rr * PP + u.pn * BM : Z + rr * 1024 + (u.pn - 16) * BM) + colt;
; #pragma unroll
;                     for (int bj = 0; bj < 2; ++bj)
; #pragma unroll
;                         for (int n = 0; n < 2; ++n) { const f32x4 v = acc[ai][bj][m][n]; u32x2 w; w.x = cvtpk(v[0], v[1]); w.y = cvtpk(v[2], v[3]); *(u32x2*)(rp + bj * HALF + n * 16) = w; } }
.LBB0_242:
	v_lshl_add_u64 v[80:81], v[80:81], 0, v[132:133]
	v_cvt_pk_bf16_f32 v75, v74, v75
	v_cvt_pk_bf16_f32 v74, v72, v73
	v_cvt_pk_bf16_f32 v72, v76, v77
	v_cvt_pk_bf16_f32 v73, v78, v79
	v_cvt_pk_bf16_f32 v67, v66, v67
	v_cvt_pk_bf16_f32 v66, v64, v65
	v_cvt_pk_bf16_f32 v64, v68, v69
	v_cvt_pk_bf16_f32 v65, v70, v71
	s_nop 1
	v_permlane16_swap_b32_e32 v72, v74
	v_permlane16_swap_b32_e32 v73, v75
	v_permlane16_swap_b32_e32 v64, v66
	v_permlane16_swap_b32_e32 v65, v67
	global_store_dwordx4 v[80:81], v[72:75], off
	global_store_dwordx4 v[80:81], v[64:67], off offset:256
	s_nop 1
	v_add_u32_e32 v64, 0x80, v146
	v_ashrrev_i32_e32 v65, 31, v64
	s_and_b64 vcc, exec, s[4:5]
	s_mov_b64 s[38:39], -1
	s_cbranch_vccnz .LBB0_244
	v_lshlrev_b64 v[66:67], 11, v[64:65]
	v_lshl_add_u64 v[66:67], s[10:11], 0, v[66:67]
	s_mov_b32 s27, s81
	v_lshl_add_u64 v[66:67], s[26:27], 1, v[66:67]
	v_lshl_add_u64 v[66:67], v[66:67], 0, s[16:17]
	s_mov_b64 s[38:39], 0

; DI unsigned cvtpk(float lo, float hi) { f32x2_t v = {lo, hi}; bf16x2_t b = __builtin_convertvector(v, bf16x2_t); return __builtin_bit_cast(unsigned, b); }
;     DI void operator()(const f32x4 (&acc)[2][2][4][2], const Unit& u, int wr, int wc, int fr, int fq) const {
;     ...
;                 for (int m = 0; m < 4; ++m) { const size_t rr = (size_t)(row0 + ai * HALF + m * 16); bf16_t* rp = (u.pn < 16 ? P + rr * PP + u.pn * BM : Z + rr * 1024 + (u.pn - 16) * BM) + colt;
; #pragma unroll
;                     for (int bj = 0; bj < 2; ++bj)
; #pragma unroll
;                         for (int n = 0; n < 2; ++n) { const f32x4 v = acc[ai][bj][m][n]; u32x2 w; w.x = cvtpk(v[0], v[1]); w.y = cvtpk(v[2], v[3]); *(u32x2*)(rp + bj * HALF + n * 16) = w; } }
.LBB0_246:
	v_lshl_add_u64 v[64:65], v[66:67], 0, v[132:133]
	v_cvt_pk_bf16_f32 v59, v58, v59
	v_cvt_pk_bf16_f32 v58, v56, v57
	v_cvt_pk_bf16_f32 v56, v60, v61
	v_cvt_pk_bf16_f32 v57, v62, v63
	v_cvt_pk_bf16_f32 v51, v50, v51
	v_cvt_pk_bf16_f32 v50, v48, v49
	v_cvt_pk_bf16_f32 v48, v52, v53
	v_cvt_pk_bf16_f32 v49, v54, v55
	s_nop 1
	v_permlane16_swap_b32_e32 v56, v58
	v_permlane16_swap_b32_e32 v57, v59
	v_permlane16_swap_b32_e32 v48, v50
	v_permlane16_swap_b32_e32 v49, v51
	global_store_dwordx4 v[64:65], v[56:59], off
	global_store_dwordx4 v[64:65], v[48:51], off offset:256
	s_nop 1
	v_add_u32_e32 v48, 0x90, v146
	v_ashrrev_i32_e32 v49, 31, v48
	s_and_b64 vcc, exec, s[4:5]
	s_mov_b64 s[38:39], -1
	s_cbranch_vccnz .LBB0_248
	v_lshlrev_b64 v[50:51], 11, v[48:49]
	v_lshl_add_u64 v[50:51], s[10:11], 0, v[50:51]
	s_mov_b32 s27, s81
	v_lshl_add_u64 v[50:51], s[26:27], 1, v[50:51]
	v_lshl_add_u64 v[50:51], v[50:51], 0, s[16:17]
	s_mov_b64 s[38:39], 0

; DI unsigned cvtpk(float lo, float hi) { f32x2_t v = {lo, hi}; bf16x2_t b = __builtin_convertvector(v, bf16x2_t); return __builtin_bit_cast(unsigned, b); }
;     DI void operator()(const f32x4 (&acc)[2][2][4][2], const Unit& u, int wr, int wc, int fr, int fq) const {
;     ...
;                 for (int m = 0; m < 4; ++m) { const size_t rr = (size_t)(row0 + ai * HALF + m * 16); bf16_t* rp = (u.pn < 16 ? P + rr * PP + u.pn * BM : Z + rr * 1024 + (u.pn - 16) * BM) + colt;
; #pragma unroll
;                     for (int bj = 0; bj < 2; ++bj)
; #pragma unroll
;                         for (int n = 0; n < 2; ++n) { const f32x4 v = acc[ai][bj][m][n]; u32x2 w; w.x = cvtpk(v[0], v[1]); w.y = cvtpk(v[2], v[3]); *(u32x2*)(rp + bj * HALF + n * 16) = w; } }
.LBB0_250:
	v_lshl_add_u64 v[48:49], v[50:51], 0, v[132:133]
	v_cvt_pk_bf16_f32 v43, v42, v43
	v_cvt_pk_bf16_f32 v42, v40, v41
	v_cvt_pk_bf16_f32 v40, v44, v45
	v_cvt_pk_bf16_f32 v41, v46, v47
	v_cvt_pk_bf16_f32 v35, v34, v35
	v_cvt_pk_bf16_f32 v34, v32, v33
	v_cvt_pk_bf16_f32 v32, v36, v37
	v_cvt_pk_bf16_f32 v33, v38, v39
	s_nop 1
	v_permlane16_swap_b32_e32 v40, v42
	v_permlane16_swap_b32_e32 v41, v43
	v_permlane16_swap_b32_e32 v32, v34
	v_permlane16_swap_b32_e32 v33, v35
	global_store_dwordx4 v[48:49], v[40:43], off
	global_store_dwordx4 v[48:49], v[32:35], off offset:256
	s_nop 1
	v_add_u32_e32 v32, 0xa0, v146
	v_ashrrev_i32_e32 v33, 31, v32
	s_and_b64 vcc, exec, s[4:5]
	s_mov_b64 s[38:39], -1
	s_cbranch_vccnz .LBB0_252
	v_lshlrev_b64 v[34:35], 11, v[32:33]
	v_lshl_add_u64 v[34:35], s[10:11], 0, v[34:35]
	s_mov_b32 s27, s81
	v_lshl_add_u64 v[34:35], s[26:27], 1, v[34:35]
	v_lshl_add_u64 v[34:35], v[34:35], 0, s[16:17]
	s_mov_b64 s[38:39], 0

; DI unsigned cvtpk(float lo, float hi) { f32x2_t v = {lo, hi}; bf16x2_t b = __builtin_convertvector(v, bf16x2_t); return __builtin_bit_cast(unsigned, b); }
;     DI void operator()(const f32x4 (&acc)[2][2][4][2], const Unit& u, int wr, int wc, int fr, int fq) const {
;     ...
;                 for (int m = 0; m < 4; ++m) { const size_t rr = (size_t)(row0 + ai * HALF + m * 16); bf16_t* rp = (u.pn < 16 ? P + rr * PP + u.pn * BM : Z + rr * 1024 + (u.pn - 16) * BM) + colt;
; #pragma unroll
;                     for (int bj = 0; bj < 2; ++bj)
; #pragma unroll
;                         for (int n = 0; n < 2; ++n) { const f32x4 v = acc[ai][bj][m][n]; u32x2 w; w.x = cvtpk(v[0], v[1]); w.y = cvtpk(v[2], v[3]); *(u32x2*)(rp + bj * HALF + n * 16) = w; } }
.LBB0_254:
	v_lshl_add_u64 v[32:33], v[34:35], 0, v[132:133]
	v_cvt_pk_bf16_f32 v27, v26, v27
	v_cvt_pk_bf16_f32 v26, v24, v25
	v_cvt_pk_bf16_f32 v24, v28, v29
	v_cvt_pk_bf16_f32 v25, v30, v31
	v_cvt_pk_bf16_f32 v19, v18, v19
	v_cvt_pk_bf16_f32 v18, v16, v17
	v_cvt_pk_bf16_f32 v16, v20, v21
	v_cvt_pk_bf16_f32 v17, v22, v23
	s_nop 1
	v_permlane16_swap_b32_e32 v24, v26
	v_permlane16_swap_b32_e32 v25, v27
	v_permlane16_swap_b32_e32 v16, v18
	v_permlane16_swap_b32_e32 v17, v19
	global_store_dwordx4 v[32:33], v[24:27], off
	global_store_dwordx4 v[32:33], v[16:19], off offset:256
	s_nop 1
	v_add_u32_e32 v16, 0xb0, v146
	v_ashrrev_i32_e32 v17, 31, v16
	s_and_b64 vcc, exec, s[4:5]
	s_mov_b64 s[4:5], -1
	s_cbranch_vccnz .LBB0_256
	v_lshlrev_b64 v[18:19], 11, v[16:17]
	v_lshl_add_u64 v[18:19], s[10:11], 0, v[18:19]
	s_mov_b32 s27, s81
	v_lshl_add_u64 v[18:19], s[26:27], 1, v[18:19]
	v_lshl_add_u64 v[18:19], v[18:19], 0, s[16:17]
	s_mov_b64 s[4:5], 0

; DI unsigned cvtpk(float lo, float hi) { f32x2_t v = {lo, hi}; bf16x2_t b = __builtin_convertvector(v, bf16x2_t); return __builtin_bit_cast(unsigned, b); }
;     DI void operator()(const f32x4 (&acc)[2][2][4][2], const Unit& u, int wr, int wc, int fr, int fq) const {
;     ...
;                 for (int m = 0; m < 4; ++m) { const size_t rr = (size_t)(row0 + ai * HALF + m * 16); bf16_t* rp = (u.pn < 16 ? P + rr * PP + u.pn * BM : Z + rr * 1024 + (u.pn - 16) * BM) + colt;
; #pragma unroll
;                     for (int bj = 0; bj < 2; ++bj)
; #pragma unroll
;                         for (int n = 0; n < 2; ++n) { const f32x4 v = acc[ai][bj][m][n]; u32x2 w; w.x = cvtpk(v[0], v[1]); w.y = cvtpk(v[2], v[3]); *(u32x2*)(rp + bj * HALF + n * 16) = w; } }
.LBB0_258:
	v_lshl_add_u64 v[16:17], v[18:19], 0, v[132:133]
	v_cvt_pk_bf16_f32 v11, v10, v11
	v_cvt_pk_bf16_f32 v10, v8, v9
	v_cvt_pk_bf16_f32 v8, v12, v13
	v_cvt_pk_bf16_f32 v9, v14, v15
	v_cvt_pk_bf16_f32 v3, v2, v3
	v_cvt_pk_bf16_f32 v2, v0, v1
	v_cvt_pk_bf16_f32 v0, v4, v5
	v_cvt_pk_bf16_f32 v1, v6, v7
	s_nop 1
	v_permlane16_swap_b32_e32 v8, v10
	v_permlane16_swap_b32_e32 v9, v11
	v_permlane16_swap_b32_e32 v0, v2
	v_permlane16_swap_b32_e32 v1, v3
	global_store_dwordx4 v[16:17], v[8:11], off
	global_store_dwordx4 v[16:17], v[0:3], off offset:256
	s_nop 1
	s_andn2_b64 vcc, exec, s[2:3]
	s_mov_b64 s[2:3], -1
	s_cbranch_vccnz .LBB0_215
